# B loop: p0 row-sum adds moved out of the QK1 segment; lgkmcnt waits capped at 14 (no reliance on counter saturation)
# baseline (speedup 1.0000x reference)
; #define SBAR() __builtin_amdgcn_sched_barrier(0)
; DEV void attn_a_item(const Params& P, int layer, int batch, int item, char* lds) {
;     ...
;     trq<0, 0>(vb, fa);
; #pragma unroll
;     for (int ks = 0; ks < 4; ++ks) p1 = __builtin_amdgcn_mfma_f32_32x32x16_bf16(kf[2 * ks + 1], qr[ks], p1, 0, 0, 0);
;     sm_exp(p0, lsum); sm_pack(p0, pa0, pa1);
;     asm volatile("s_waitcnt lgkmcnt(0)" ::: "memory"); SBAR();
;     trq<0, 2>(vb, fb);
;     mmaq(o[0], o[1], fa, pa0, pa1);
;     sm_exp(p1, lsum);
;     asm volatile("s_waitcnt lgkmcnt(0)" ::: "memory"); SBAR();
;     trq<2, 0>(vb, fa);
;     mmaq(o[2], o[3], fb, pa0, pa1);
;     sm_pack(p1, pa2, pa3);
;     asm volatile("s_waitcnt lgkmcnt(0)" ::: "memory"); SBAR();
;     trq<2, 2>(vb, fb);
;     mmaq(o[0], o[1], fa, pa2, pa3);
;     asm volatile("s_waitcnt lgkmcnt(0)" ::: "memory"); SBAR();
;     mmaq(o[2], o[3], fb, pa2, pa3);
;     asm volatile("s_waitcnt vmcnt(0)" ::: "memory");
;     __syncthreads();
.Ldfa_drain1:
	ds_read_b64_tr_b16 v[218:219], v173 offset:16384
	ds_read_b64_tr_b16 v[220:221], v173 offset:18432
	ds_read_b64_tr_b16 v[222:223], v173 offset:16896
	ds_read_b64_tr_b16 v[224:225], v173 offset:18944
	ds_read_b64_tr_b16 v[232:233], v173 offset:17408
	ds_read_b64_tr_b16 v[234:235], v173 offset:19456
	ds_read_b64_tr_b16 v[236:237], v173 offset:17920
	ds_read_b64_tr_b16 v[238:239], v173 offset:19968
	ds_read_b64_tr_b16 v[240:241], v173 offset:20480
	ds_read_b64_tr_b16 v[242:243], v173 offset:22528
	ds_read_b64_tr_b16 v[244:245], v173 offset:20992
	ds_read_b64_tr_b16 v[246:247], v173 offset:23040
	ds_read_b64_tr_b16 v[248:249], v173 offset:21504
	ds_read_b64_tr_b16 v[250:251], v173 offset:23552
	ds_read_b64_tr_b16 v[194:195], v173 offset:22016
	ds_read_b64_tr_b16 v[196:197], v173 offset:24064
	v_mfma_f32_32x32x16_bf16 v[48:63], v[150:153], v[202:205], v[48:63]
	ds_read_b64_tr_b16 v[202:203], v173 offset:24576
	ds_read_b64_tr_b16 v[204:205], v173 offset:26624
	v_mfma_f32_32x32x16_bf16 v[32:47], v[150:153], v[206:209], v[32:47]
	ds_read_b64_tr_b16 v[206:207], v173 offset:25088
	ds_read_b64_tr_b16 v[208:209], v173 offset:27136
	v_mfma_f32_32x32x16_bf16 v[16:31], v[150:153], v[210:213], v[16:31]
	ds_read_b64_tr_b16 v[210:211], v173 offset:25600
	ds_read_b64_tr_b16 v[212:213], v173 offset:27648
	v_mfma_f32_32x32x16_bf16 v[0:15], v[150:153], v[214:217], v[0:15]
	ds_read_b64_tr_b16 v[214:215], v173 offset:26112
	ds_read_b64_tr_b16 v[216:217], v173 offset:28160
	s_waitcnt lgkmcnt(14)
	v_mfma_f32_32x32x16_bf16 v[48:63], v[176:179], v[218:221], v[48:63]
	ds_read_b64_tr_b16 v[218:219], v173 offset:28672
	ds_read_b64_tr_b16 v[220:221], v173 offset:30720
	s_waitcnt lgkmcnt(14)
	v_mfma_f32_32x32x16_bf16 v[32:47], v[176:179], v[222:225], v[32:47]
	ds_read_b64_tr_b16 v[222:223], v173 offset:29184
	ds_read_b64_tr_b16 v[224:225], v173 offset:31232
	s_waitcnt lgkmcnt(14)
	v_mfma_f32_32x32x16_bf16 v[16:31], v[176:179], v[232:235], v[16:31]
	ds_read_b64_tr_b16 v[232:233], v173 offset:29696
	ds_read_b64_tr_b16 v[234:235], v173 offset:31744
	s_waitcnt lgkmcnt(14)
	v_mfma_f32_32x32x16_bf16 v[0:15], v[176:179], v[236:239], v[0:15]
	ds_read_b64_tr_b16 v[236:237], v173 offset:30208
	ds_read_b64_tr_b16 v[238:239], v173 offset:32256
	s_waitcnt lgkmcnt(14)
	v_mfma_f32_32x32x16_bf16 v[48:63], v[180:183], v[240:243], v[48:63]
	s_waitcnt lgkmcnt(14)
	v_mfma_f32_32x32x16_bf16 v[32:47], v[180:183], v[244:247], v[32:47]
	s_waitcnt lgkmcnt(14)
	v_mfma_f32_32x32x16_bf16 v[16:31], v[180:183], v[248:251], v[16:31]
	s_waitcnt lgkmcnt(14)
	v_mfma_f32_32x32x16_bf16 v[0:15], v[180:183], v[194:197], v[0:15]
	s_waitcnt lgkmcnt(14)
	v_mfma_f32_32x32x16_bf16 v[48:63], v[198:201], v[202:205], v[48:63]
	s_waitcnt lgkmcnt(12)
	v_mfma_f32_32x32x16_bf16 v[32:47], v[198:201], v[206:209], v[32:47]
	s_waitcnt lgkmcnt(10)
	v_mfma_f32_32x32x16_bf16 v[16:31], v[198:201], v[210:213], v[16:31]
	s_waitcnt lgkmcnt(8)
	v_mfma_f32_32x32x16_bf16 v[0:15], v[198:201], v[214:217], v[0:15]
	s_waitcnt lgkmcnt(6)
	v_mfma_f32_32x32x16_bf16 v[48:63], v[154:157], v[218:221], v[48:63]
	s_waitcnt lgkmcnt(4)
	v_mfma_f32_32x32x16_bf16 v[32:47], v[154:157], v[222:225], v[32:47]
	s_waitcnt lgkmcnt(2)
	v_mfma_f32_32x32x16_bf16 v[16:31], v[154:157], v[232:235], v[16:31]
	s_waitcnt lgkmcnt(0)
	v_mfma_f32_32x32x16_bf16 v[0:15], v[154:157], v[236:239], v[0:15]
	v_add_f32_e32 v167, v167, v80
	v_add_f32_e32 v167, v167, v81
	v_add_f32_e32 v167, v167, v82
	v_add_f32_e32 v167, v167, v83
	v_add_f32_e32 v167, v167, v84
	v_add_f32_e32 v167, v167, v85
	v_add_f32_e32 v167, v167, v86
	v_add_f32_e32 v167, v167, v87
	v_add_f32_e32 v167, v167, v88
	v_add_f32_e32 v167, v167, v89
	v_add_f32_e32 v167, v167, v90
	v_add_f32_e32 v167, v167, v91
	v_add_f32_e32 v167, v167, v92
	v_add_f32_e32 v167, v167, v93
	v_add_f32_e32 v167, v167, v94
	v_add_f32_e32 v167, v167, v95
	s_branch .LBB0_383
; #define SBAR() __builtin_amdgcn_sched_barrier(0)
; DEV void attn_a_item(const Params& P, int layer, int batch, int item, char* lds) {
;     ...
;     trq<0, 0>(vb, fa);
; #pragma unroll
;     for (int ks = 0; ks < 4; ++ks) p1 = __builtin_amdgcn_mfma_f32_32x32x16_bf16(kf[2 * ks + 1], qr[ks], p1, 0, 0, 0);
;     sm_exp(p0, lsum); sm_pack(p0, pa0, pa1);
;     asm volatile("s_waitcnt lgkmcnt(0)" ::: "memory"); SBAR();
;     trq<0, 2>(vb, fb);
;     mmaq(o[0], o[1], fa, pa0, pa1);
;     sm_exp(p1, lsum);
;     asm volatile("s_waitcnt lgkmcnt(0)" ::: "memory"); SBAR();
;     trq<2, 0>(vb, fa);
;     mmaq(o[2], o[3], fb, pa0, pa1);
;     sm_pack(p1, pa2, pa3);
;     asm volatile("s_waitcnt lgkmcnt(0)" ::: "memory"); SBAR();
;     trq<2, 2>(vb, fb);
;     mmaq(o[0], o[1], fa, pa2, pa3);
;     asm volatile("s_waitcnt lgkmcnt(0)" ::: "memory"); SBAR();
;     mmaq(o[2], o[3], fb, pa2, pa3);
;     asm volatile("s_waitcnt vmcnt(0)" ::: "memory");
;     __syncthreads();
.Ldfa_drain0_pre:
.Ldfa_drain0:
	ds_read_b64_tr_b16 v[218:219], v173 offset:0
	ds_read_b64_tr_b16 v[220:221], v173 offset:2048
	ds_read_b64_tr_b16 v[222:223], v173 offset:512
	ds_read_b64_tr_b16 v[224:225], v173 offset:2560
	ds_read_b64_tr_b16 v[232:233], v173 offset:1024
	ds_read_b64_tr_b16 v[234:235], v173 offset:3072
	ds_read_b64_tr_b16 v[236:237], v173 offset:1536
	ds_read_b64_tr_b16 v[238:239], v173 offset:3584
	ds_read_b64_tr_b16 v[240:241], v173 offset:4096
	ds_read_b64_tr_b16 v[242:243], v173 offset:6144
	ds_read_b64_tr_b16 v[244:245], v173 offset:4608
	ds_read_b64_tr_b16 v[246:247], v173 offset:6656
	ds_read_b64_tr_b16 v[248:249], v173 offset:5120
	ds_read_b64_tr_b16 v[250:251], v173 offset:7168
	ds_read_b64_tr_b16 v[194:195], v173 offset:5632
	ds_read_b64_tr_b16 v[196:197], v173 offset:7680
	v_mfma_f32_32x32x16_bf16 v[48:63], v[154:157], v[202:205], v[48:63]
	ds_read_b64_tr_b16 v[202:203], v173 offset:8192
	ds_read_b64_tr_b16 v[204:205], v173 offset:10240
	v_mfma_f32_32x32x16_bf16 v[32:47], v[154:157], v[206:209], v[32:47]
	ds_read_b64_tr_b16 v[206:207], v173 offset:8704
	ds_read_b64_tr_b16 v[208:209], v173 offset:10752
	v_mfma_f32_32x32x16_bf16 v[16:31], v[154:157], v[210:213], v[16:31]
	ds_read_b64_tr_b16 v[210:211], v173 offset:9216
	ds_read_b64_tr_b16 v[212:213], v173 offset:11264
	v_mfma_f32_32x32x16_bf16 v[0:15], v[154:157], v[214:217], v[0:15]
	ds_read_b64_tr_b16 v[214:215], v173 offset:9728
	ds_read_b64_tr_b16 v[216:217], v173 offset:11776
	s_waitcnt lgkmcnt(14)
	v_mfma_f32_32x32x16_bf16 v[48:63], v[176:179], v[218:221], v[48:63]
	ds_read_b64_tr_b16 v[218:219], v173 offset:12288
	ds_read_b64_tr_b16 v[220:221], v173 offset:14336
	s_waitcnt lgkmcnt(14)
	v_mfma_f32_32x32x16_bf16 v[32:47], v[176:179], v[222:225], v[32:47]
	ds_read_b64_tr_b16 v[222:223], v173 offset:12800
	ds_read_b64_tr_b16 v[224:225], v173 offset:14848
	s_waitcnt lgkmcnt(14)
	v_mfma_f32_32x32x16_bf16 v[16:31], v[176:179], v[232:235], v[16:31]
	ds_read_b64_tr_b16 v[232:233], v173 offset:13312
	ds_read_b64_tr_b16 v[234:235], v173 offset:15360
	s_waitcnt lgkmcnt(14)
	v_mfma_f32_32x32x16_bf16 v[0:15], v[176:179], v[236:239], v[0:15]
	ds_read_b64_tr_b16 v[236:237], v173 offset:13824
	ds_read_b64_tr_b16 v[238:239], v173 offset:15872
	s_waitcnt lgkmcnt(14)
	v_mfma_f32_32x32x16_bf16 v[48:63], v[180:183], v[240:243], v[48:63]
	s_waitcnt lgkmcnt(14)
	v_mfma_f32_32x32x16_bf16 v[32:47], v[180:183], v[244:247], v[32:47]
	s_waitcnt lgkmcnt(14)
	v_mfma_f32_32x32x16_bf16 v[16:31], v[180:183], v[248:251], v[16:31]
	s_waitcnt lgkmcnt(14)
	v_mfma_f32_32x32x16_bf16 v[0:15], v[180:183], v[194:197], v[0:15]
	s_waitcnt lgkmcnt(14)
	v_mfma_f32_32x32x16_bf16 v[48:63], v[186:189], v[202:205], v[48:63]
	s_waitcnt lgkmcnt(12)
	v_mfma_f32_32x32x16_bf16 v[32:47], v[186:189], v[206:209], v[32:47]
	s_waitcnt lgkmcnt(10)
	v_mfma_f32_32x32x16_bf16 v[16:31], v[186:189], v[210:213], v[16:31]
	s_waitcnt lgkmcnt(8)
	v_mfma_f32_32x32x16_bf16 v[0:15], v[186:189], v[214:217], v[0:15]
	s_waitcnt lgkmcnt(6)
	v_mfma_f32_32x32x16_bf16 v[48:63], v[150:153], v[218:221], v[48:63]
	s_waitcnt lgkmcnt(4)
	v_mfma_f32_32x32x16_bf16 v[32:47], v[150:153], v[222:225], v[32:47]
	s_waitcnt lgkmcnt(2)
	v_mfma_f32_32x32x16_bf16 v[16:31], v[150:153], v[232:235], v[16:31]
	s_waitcnt lgkmcnt(0)
	v_mfma_f32_32x32x16_bf16 v[0:15], v[150:153], v[236:239], v[0:15]
	v_add_f32_e32 v167, v167, v80
	v_add_f32_e32 v167, v167, v81
	v_add_f32_e32 v167, v167, v82
	v_add_f32_e32 v167, v167, v83
	v_add_f32_e32 v167, v167, v84
	v_add_f32_e32 v167, v167, v85
	v_add_f32_e32 v167, v167, v86
	v_add_f32_e32 v167, v167, v87
	v_add_f32_e32 v167, v167, v88
	v_add_f32_e32 v167, v167, v89
	v_add_f32_e32 v167, v167, v90
	v_add_f32_e32 v167, v167, v91
	v_add_f32_e32 v167, v167, v92
	v_add_f32_e32 v167, v167, v93
	v_add_f32_e32 v167, v167, v94
	v_add_f32_e32 v167, v167, v95
	s_branch .LBB0_383

; #define SBAR() __builtin_amdgcn_sched_barrier(0)
; #define SGB(mask, n) __builtin_amdgcn_sched_group_barrier(mask, n, 0)
; #define BLOAD(b, k0) do { _Pragma("unroll") for (int i = 0; i < 3; ++i) glds16(Kh + (long)(k0) * 768 + bkoff[i], K_lds + (b) * 24576 + ldst[i]); \
;     _Pragma("unroll") for (int i = 0; i < 2; ++i) glds16(Vh + (long)(k0) * 512 + bvoff[i], V_lds + (b) * 16384 + ldst[i]); } while (0)
; DEV void attn_b_item(const Params& P, int layer, int batch, int item, char* lds) {
;     ...
;   for (int j = 0; j < NT; ++j) {
;     const char* Ks = K_lds + (j & 1) * 24576;
;     const int vb = vb0 + (j & 1) * 16384;
;     f32x16 p0, p1;
; #pragma unroll
;     for (int r = 0; r < 16; ++r) { p0[r] = 0.f; p1[r] = 0.f; }
;     bf16x8 pa0, pa1, pa2, pa3;
;     s16x4 fa[8], fb[8];
;     {
;       bf16x8 kf[12];
; #pragma unroll
;       for (int ks = 0; ks < 12; ++ks) kf[ks] = *reinterpret_cast<const bf16x8*>(Ks + kq + (((ks * 2 + hi) ^ ksw) << 4));
; #pragma unroll
;       for (int ks = 0; ks < 12; ++ks) p0 = __builtin_amdgcn_mfma_f32_32x32x16_bf16(kf[ks], qr[ks], p0, 0, 0, 0);
;       SGB(0x100, 4); SGB(0x008, 2); SGB(0x100, 2); SGB(0x008, 2); SGB(0x100, 2); SGB(0x008, 2); SGB(0x100, 2); SGB(0x008, 2); SGB(0x100, 2); SGB(0x008, 4);
;     }
;     SBAR();
;     if (j + 1 < NT) BLOAD((j + 1) & 1, (j + 1) * 64);
;     SBAR();
;     {
;       trq<0, 0>(vb, fa);
;       bf16x8 kf[12];
; #pragma unroll
;       for (int ks = 0; ks < 12; ++ks) kf[ks] = *reinterpret_cast<const bf16x8*>(Ks + kq + 32 * 384 + (((ks * 2 + hi) ^ ksw) << 4));
; #pragma unroll
;       for (int ks = 0; ks < 12; ++ks) p1 = __builtin_amdgcn_mfma_f32_32x32x16_bf16(kf[ks], qr[ks], p1, 0, 0, 0);
;       sm_exp(p0, lsum); sm_pack(p0, pa0, pa1);
;     }
;     asm volatile("s_waitcnt lgkmcnt(0)" ::: "memory"); SBAR();
;     trq<0, 2>(vb, fb);
;     mmaq(o[0], o[1], fa, pa0, pa1);
;     sm_exp(p1, lsum);
;     asm volatile("s_waitcnt lgkmcnt(0)" ::: "memory"); SBAR();
;     trq<2, 0>(vb, fa);
;     mmaq(o[2], o[3], fb, pa0, pa1);
;     sm_pack(p1, pa2, pa3);
;     asm volatile("s_waitcnt lgkmcnt(0)" ::: "memory"); SBAR();
;     trq<2, 2>(vb, fb);
;     mmaq(o[0], o[1], fa, pa2, pa3);
;     asm volatile("s_waitcnt lgkmcnt(0)" ::: "memory"); SBAR();
;     mmaq(o[2], o[3], fb, pa2, pa3);
;     asm volatile("s_waitcnt vmcnt(0)" ::: "memory");
;     __syncthreads();
;   }
.Lmla_loop:
	ds_read_b128 v[218:221], v169 offset:0
	ds_read_b128 v[232:235], v170 offset:0
	ds_read_b128 v[236:239], v171 offset:0
	ds_read_b128 v[240:243], v172 offset:0
	ds_read_b128 v[244:247], v169 offset:128
	ds_read_b128 v[248:251], v170 offset:128
	v_mfma_f32_32x32x16_bf16 v[48:63], v[198:201], v[202:205], v[48:63]
	ds_read_b128 v[202:205], v171 offset:128
	v_mfma_f32_32x32x16_bf16 v[32:47], v[198:201], v[206:209], v[32:47]
	ds_read_b128 v[206:209], v172 offset:128
	v_mfma_f32_32x32x16_bf16 v[16:31], v[198:201], v[210:213], v[16:31]
	ds_read_b128 v[210:213], v169 offset:256
	v_mfma_f32_32x32x16_bf16 v[0:15], v[198:201], v[214:217], v[0:15]
	ds_read_b128 v[214:217], v170 offset:256
	s_waitcnt lgkmcnt(9)
	v_mfma_f32_32x32x16_bf16 v[64:79], v[218:221], v[96:99], 0
	ds_read_b128 v[218:221], v171 offset:256
	v_add_f32_e32 v182, v182, v80
	v_add_f32_e32 v182, v182, v81
	s_waitcnt lgkmcnt(9)
	v_mfma_f32_32x32x16_bf16 v[64:79], v[232:235], v[100:103], v[64:79]
	ds_read_b128 v[232:235], v172 offset:256
	v_add_f32_e32 v182, v182, v82
	s_add_u32 m0, s100, 0x6000
	s_nop 0
	global_load_lds_dwordx4 v146, s[68:69]
	s_add_u32 m0, s101, 0x4000
	s_nop 0
	global_load_lds_dwordx4 v148, s[70:71]
	s_add_u32 m0, s100, 0x8000
	s_nop 0
	global_load_lds_dwordx4 v150, s[68:69]
	s_add_u32 m0, s101, 0x6000
	s_nop 0
	global_load_lds_dwordx4 v152, s[70:71]
	s_add_u32 m0, s100, 0xa000
	s_nop 0
	global_load_lds_dwordx4 v154, s[68:69]
	s_add_u32 s68, s68, 0x18000
	s_addc_u32 s69, s69, 0
	s_add_u32 s70, s70, 0x10000
	s_addc_u32 s71, s71, 0
	s_waitcnt lgkmcnt(9)
	v_mfma_f32_32x32x16_bf16 v[64:79], v[236:239], v[104:107], v[64:79]
	ds_read_b128 v[236:239], v169 offset:12288
	v_add_f32_e32 v182, v182, v83
	s_waitcnt lgkmcnt(9)
	v_mfma_f32_32x32x16_bf16 v[64:79], v[240:243], v[108:111], v[64:79]
	ds_read_b128 v[240:243], v170 offset:12288
	v_add_f32_e32 v182, v182, v84
	v_add_f32_e32 v182, v182, v85
	s_waitcnt lgkmcnt(9)
	v_mfma_f32_32x32x16_bf16 v[64:79], v[244:247], v[112:115], v[64:79]
	ds_read_b128 v[244:247], v171 offset:12288
	v_add_f32_e32 v182, v182, v86
	s_waitcnt lgkmcnt(9)
	v_mfma_f32_32x32x16_bf16 v[64:79], v[248:251], v[116:119], v[64:79]
	ds_read_b128 v[248:251], v172 offset:12288
	v_add_f32_e32 v182, v182, v87
	s_waitcnt lgkmcnt(9)
	v_mfma_f32_32x32x16_bf16 v[64:79], v[202:205], v[120:123], v[64:79]
	ds_read_b128 v[202:205], v169 offset:12416
	v_add_f32_e32 v182, v182, v88
	v_add_f32_e32 v182, v182, v89
	s_waitcnt lgkmcnt(9)
	v_mfma_f32_32x32x16_bf16 v[64:79], v[206:209], v[124:127], v[64:79]
	ds_read_b128 v[206:209], v170 offset:12416
	v_add_f32_e32 v182, v182, v90
	s_waitcnt lgkmcnt(9)
	v_mfma_f32_32x32x16_bf16 v[64:79], v[210:213], v[128:131], v[64:79]
	ds_read_b128 v[210:213], v171 offset:12416
	v_add_f32_e32 v182, v182, v91
	s_waitcnt lgkmcnt(9)
	v_mfma_f32_32x32x16_bf16 v[64:79], v[214:217], v[132:135], v[64:79]
	ds_read_b128 v[214:217], v172 offset:12416
	v_add_f32_e32 v182, v182, v92
	v_add_f32_e32 v182, v182, v93
	s_waitcnt lgkmcnt(9)
	v_mfma_f32_32x32x16_bf16 v[64:79], v[218:221], v[136:139], v[64:79]
	ds_read_b128 v[218:221], v169 offset:12544
	v_add_f32_e32 v182, v182, v94
	s_waitcnt lgkmcnt(9)
	v_mfma_f32_32x32x16_bf16 v[64:79], v[232:235], v[140:143], v[64:79]
	ds_read_b128 v[232:235], v170 offset:12544
	v_add_f32_e32 v182, v182, v95
	s_waitcnt lgkmcnt(9)
	v_mfma_f32_32x32x16_bf16 v[80:95], v[236:239], v[96:99], 0
	ds_read_b128 v[236:239], v171 offset:12544
	s_waitcnt lgkmcnt(9)
	v_mfma_f32_32x32x16_bf16 v[80:95], v[240:243], v[100:103], v[80:95]
	ds_read_b128 v[240:243], v172 offset:12544
	s_waitcnt lgkmcnt(9)
	v_mfma_f32_32x32x16_bf16 v[80:95], v[244:247], v[104:107], v[80:95]
	ds_read_b64_tr_b16 v[244:245], v166 offset:0
	ds_read_b64_tr_b16 v[246:247], v166 offset:2048
	s_waitcnt lgkmcnt(10)
	v_mfma_f32_32x32x16_bf16 v[80:95], v[248:251], v[108:111], v[80:95]
	ds_read_b64_tr_b16 v[248:249], v166 offset:512
	ds_read_b64_tr_b16 v[250:251], v166 offset:2560
	v_exp_f32_e32 v64, v64
	v_exp_f32_e32 v65, v65
	s_waitcnt lgkmcnt(11)
	v_mfma_f32_32x32x16_bf16 v[80:95], v[202:205], v[112:115], v[80:95]
	ds_read_b64_tr_b16 v[202:203], v166 offset:1024
	ds_read_b64_tr_b16 v[204:205], v166 offset:3072
	v_exp_f32_e32 v66, v66
	v_exp_f32_e32 v67, v67
	s_waitcnt lgkmcnt(12)
	v_mfma_f32_32x32x16_bf16 v[80:95], v[206:209], v[116:119], v[80:95]
	ds_read_b64_tr_b16 v[206:207], v166 offset:1536
	ds_read_b64_tr_b16 v[208:209], v166 offset:3584
	v_exp_f32_e32 v68, v68
	v_exp_f32_e32 v69, v69
	s_waitcnt lgkmcnt(13)
	v_mfma_f32_32x32x16_bf16 v[80:95], v[210:213], v[120:123], v[80:95]
	ds_read_b64_tr_b16 v[210:211], v166 offset:4096
	ds_read_b64_tr_b16 v[212:213], v166 offset:6144
	v_exp_f32_e32 v70, v70
	v_exp_f32_e32 v71, v71
	s_waitcnt lgkmcnt(14)
	v_mfma_f32_32x32x16_bf16 v[80:95], v[214:217], v[124:127], v[80:95]
	ds_read_b64_tr_b16 v[214:215], v166 offset:4608
	ds_read_b64_tr_b16 v[216:217], v166 offset:6656
	v_cvt_pk_bf16_f32 v174, v64, v65
	v_exp_f32_e32 v72, v72
	v_exp_f32_e32 v73, v73
	s_waitcnt lgkmcnt(14)
	v_mfma_f32_32x32x16_bf16 v[80:95], v[218:221], v[128:131], v[80:95]
	ds_read_b64_tr_b16 v[218:219], v166 offset:5120
	ds_read_b64_tr_b16 v[220:221], v166 offset:7168
	v_cvt_pk_bf16_f32 v175, v66, v67
	v_exp_f32_e32 v74, v74
	v_exp_f32_e32 v75, v75
	s_waitcnt lgkmcnt(14)
	v_mfma_f32_32x32x16_bf16 v[80:95], v[232:235], v[132:135], v[80:95]
	ds_read_b64_tr_b16 v[232:233], v166 offset:5632
	ds_read_b64_tr_b16 v[234:235], v166 offset:7680
	v_cvt_pk_bf16_f32 v176, v68, v69
	v_exp_f32_e32 v76, v76
	v_exp_f32_e32 v77, v77
	s_waitcnt lgkmcnt(14)
; #define SBAR() __builtin_amdgcn_sched_barrier(0)
; DEV void attn_b_item(const Params& P, int layer, int batch, int item, char* lds) {
;     ...
;     {
;       trq<0, 0>(vb, fa);
;       bf16x8 kf[12];
; #pragma unroll
;       for (int ks = 0; ks < 12; ++ks) kf[ks] = *reinterpret_cast<const bf16x8*>(Ks + kq + 32 * 384 + (((ks * 2 + hi) ^ ksw) << 4));
; #pragma unroll
;       for (int ks = 0; ks < 12; ++ks) p1 = __builtin_amdgcn_mfma_f32_32x32x16_bf16(kf[ks], qr[ks], p1, 0, 0, 0);
;       sm_exp(p0, lsum); sm_pack(p0, pa0, pa1);
;     }
;     asm volatile("s_waitcnt lgkmcnt(0)" ::: "memory"); SBAR();
;     trq<0, 2>(vb, fb);
;     mmaq(o[0], o[1], fa, pa0, pa1);
;     sm_exp(p1, lsum);
;     asm volatile("s_waitcnt lgkmcnt(0)" ::: "memory"); SBAR();
;     trq<2, 0>(vb, fa);
;     mmaq(o[2], o[3], fb, pa0, pa1);
;     sm_pack(p1, pa2, pa3);
;     asm volatile("s_waitcnt lgkmcnt(0)" ::: "memory"); SBAR();
;     trq<2, 2>(vb, fb);
;     mmaq(o[0], o[1], fa, pa2, pa3);
;     asm volatile("s_waitcnt lgkmcnt(0)" ::: "memory"); SBAR();
;     mmaq(o[2], o[3], fb, pa2, pa3);
;     asm volatile("s_waitcnt vmcnt(0)" ::: "memory");
;     __syncthreads();
;   }
	v_mfma_f32_32x32x16_bf16 v[80:95], v[236:239], v[136:139], v[80:95]
	ds_read_b64_tr_b16 v[236:237], v166 offset:8192
	ds_read_b64_tr_b16 v[238:239], v166 offset:10240
	v_cvt_pk_bf16_f32 v177, v70, v71
	v_exp_f32_e32 v78, v78
	v_exp_f32_e32 v79, v79
	s_waitcnt lgkmcnt(14)
	v_mfma_f32_32x32x16_bf16 v[80:95], v[240:243], v[140:143], v[80:95]
	ds_read_b64_tr_b16 v[240:241], v166 offset:8704
	ds_read_b64_tr_b16 v[242:243], v166 offset:10752
	v_cvt_pk_bf16_f32 v178, v72, v73
	v_cvt_pk_bf16_f32 v179, v74, v75
	v_cvt_pk_bf16_f32 v180, v76, v77
	v_cvt_pk_bf16_f32 v181, v78, v79
	s_waitcnt lgkmcnt(14)
	v_mfma_f32_32x32x16_bf16 v[48:63], v[174:177], v[244:247], v[48:63]
	ds_read_b64_tr_b16 v[244:245], v166 offset:9216
	ds_read_b64_tr_b16 v[246:247], v166 offset:11264
	v_add_f32_e32 v182, v182, v64
	v_add_f32_e32 v182, v182, v65
	v_add_f32_e32 v182, v182, v66
	v_add_f32_e32 v182, v182, v67
	s_waitcnt lgkmcnt(14)
	v_mfma_f32_32x32x16_bf16 v[32:47], v[174:177], v[248:251], v[32:47]
	ds_read_b64_tr_b16 v[248:249], v166 offset:9728
	ds_read_b64_tr_b16 v[250:251], v166 offset:11776
	v_add_f32_e32 v182, v182, v68
	v_add_f32_e32 v182, v182, v69
	v_add_f32_e32 v182, v182, v70
	v_add_f32_e32 v182, v182, v71
	s_waitcnt lgkmcnt(14)
	v_mfma_f32_32x32x16_bf16 v[16:31], v[174:177], v[202:205], v[16:31]
	ds_read_b64_tr_b16 v[202:203], v166 offset:12288
	ds_read_b64_tr_b16 v[204:205], v166 offset:14336
	v_add_f32_e32 v182, v182, v72
	v_add_f32_e32 v182, v182, v73
	v_add_f32_e32 v182, v182, v74
	v_add_f32_e32 v182, v182, v75
	s_waitcnt lgkmcnt(14)
	v_mfma_f32_32x32x16_bf16 v[0:15], v[174:177], v[206:209], v[0:15]
	ds_read_b64_tr_b16 v[206:207], v166 offset:12800
	ds_read_b64_tr_b16 v[208:209], v166 offset:14848
	v_exp_f32_e32 v80, v80
	v_exp_f32_e32 v81, v81
	v_exp_f32_e32 v82, v82
	s_waitcnt lgkmcnt(14)
	v_mfma_f32_32x32x16_bf16 v[48:63], v[178:181], v[210:213], v[48:63]
	ds_read_b64_tr_b16 v[210:211], v166 offset:13312
	ds_read_b64_tr_b16 v[212:213], v166 offset:15360
	v_exp_f32_e32 v83, v83
	v_exp_f32_e32 v84, v84
	v_exp_f32_e32 v85, v85
	s_waitcnt lgkmcnt(14)
	v_mfma_f32_32x32x16_bf16 v[32:47], v[178:181], v[214:217], v[32:47]
	ds_read_b64_tr_b16 v[214:215], v166 offset:13824
	ds_read_b64_tr_b16 v[216:217], v166 offset:15872
	v_exp_f32_e32 v86, v86
	v_exp_f32_e32 v87, v87
	v_exp_f32_e32 v88, v88
	s_waitcnt lgkmcnt(14)
	v_mfma_f32_32x32x16_bf16 v[16:31], v[178:181], v[218:221], v[16:31]
	v_cvt_pk_bf16_f32 v194, v80, v81
	v_cvt_pk_bf16_f32 v195, v82, v83
	v_exp_f32_e32 v89, v89
	v_exp_f32_e32 v90, v90
	v_exp_f32_e32 v91, v91
	s_waitcnt lgkmcnt(14)
	v_mfma_f32_32x32x16_bf16 v[0:15], v[178:181], v[232:235], v[0:15]
	v_cvt_pk_bf16_f32 v196, v84, v85
	v_cvt_pk_bf16_f32 v197, v86, v87
	v_exp_f32_e32 v92, v92
	v_exp_f32_e32 v93, v93
	s_waitcnt lgkmcnt(14)
	v_mfma_f32_32x32x16_bf16 v[48:63], v[194:197], v[236:239], v[48:63]
	v_exp_f32_e32 v94, v94
	v_exp_f32_e32 v95, v95
	s_waitcnt lgkmcnt(12)
	v_mfma_f32_32x32x16_bf16 v[32:47], v[194:197], v[240:243], v[32:47]
	v_cvt_pk_bf16_f32 v198, v88, v89
	v_cvt_pk_bf16_f32 v199, v90, v91
	v_add_f32_e32 v182, v182, v76
	v_add_f32_e32 v182, v182, v77
	s_waitcnt lgkmcnt(10)
	v_mfma_f32_32x32x16_bf16 v[16:31], v[194:197], v[244:247], v[16:31]
	v_cvt_pk_bf16_f32 v200, v92, v93
	v_cvt_pk_bf16_f32 v201, v94, v95
	v_add_f32_e32 v182, v182, v78
	v_add_f32_e32 v182, v182, v79
	s_waitcnt lgkmcnt(8)
	v_mfma_f32_32x32x16_bf16 v[0:15], v[194:197], v[248:251], v[0:15]
	s_waitcnt lgkmcnt(0)
	s_waitcnt vmcnt(0)
	s_barrier
	ds_read_b128 v[218:221], v169 offset:24576
	ds_read_b128 v[232:235], v170 offset:24576
	ds_read_b128 v[236:239], v171 offset:24576
	ds_read_b128 v[240:243], v172 offset:24576
	ds_read_b128 v[244:247], v169 offset:24704
	ds_read_b128 v[248:251], v170 offset:24704
	v_mfma_f32_32x32x16_bf16 v[48:63], v[198:201], v[202:205], v[48:63]
	ds_read_b128 v[202:205], v171 offset:24704
	v_mfma_f32_32x32x16_bf16 v[32:47], v[198:201], v[206:209], v[32:47]
	ds_read_b128 v[206:209], v172 offset:24704
	v_mfma_f32_32x32x16_bf16 v[16:31], v[198:201], v[210:213], v[16:31]
	ds_read_b128 v[210:213], v169 offset:24832
	v_mfma_f32_32x32x16_bf16 v[0:15], v[198:201], v[214:217], v[0:15]
	ds_read_b128 v[214:217], v170 offset:24832
	s_waitcnt lgkmcnt(9)
	v_mfma_f32_32x32x16_bf16 v[64:79], v[218:221], v[96:99], 0
	ds_read_b128 v[218:221], v171 offset:24832
	v_add_f32_e32 v182, v182, v80
	v_add_f32_e32 v182, v182, v81
	s_waitcnt lgkmcnt(9)
	v_mfma_f32_32x32x16_bf16 v[64:79], v[232:235], v[100:103], v[64:79]
	ds_read_b128 v[232:235], v172 offset:24832
	v_add_f32_e32 v182, v182, v82
	s_add_u32 s22, s65, 2
	s_cmp_ge_u32 s22, s50
	s_cbranch_scc1 .Lmla_skipdma_o
	s_add_u32 m0, s100, 0x0
	s_nop 0
	global_load_lds_dwordx4 v146, s[68:69]
	s_add_u32 m0, s101, 0x0
	s_nop 0
	global_load_lds_dwordx4 v148, s[70:71]
	s_add_u32 m0, s100, 0x2000
	s_nop 0
	global_load_lds_dwordx4 v150, s[68:69]
	s_add_u32 m0, s101, 0x2000
	s_nop 0
	global_load_lds_dwordx4 v152, s[70:71]
	s_add_u32 m0, s100, 0x4000
	s_nop 0
	global_load_lds_dwordx4 v154, s[68:69]
	s_add_u32 s68, s68, 0x18000
	s_addc_u32 s69, s69, 0
	s_add_u32 s70, s70, 0x10000
	s_addc_u32 s71, s71, 0
; #define SBAR() __builtin_amdgcn_sched_barrier(0)
; #define SGB(mask, n) __builtin_amdgcn_sched_group_barrier(mask, n, 0)
; #define BLOAD(b, k0) do { _Pragma("unroll") for (int i = 0; i < 3; ++i) glds16(Kh + (long)(k0) * 768 + bkoff[i], K_lds + (b) * 24576 + ldst[i]); \
;     _Pragma("unroll") for (int i = 0; i < 2; ++i) glds16(Vh + (long)(k0) * 512 + bvoff[i], V_lds + (b) * 16384 + ldst[i]); } while (0)
; DEV void attn_b_item(const Params& P, int layer, int batch, int item, char* lds) {
;     ...
;     {
;       bf16x8 kf[12];
; #pragma unroll
;       for (int ks = 0; ks < 12; ++ks) kf[ks] = *reinterpret_cast<const bf16x8*>(Ks + kq + (((ks * 2 + hi) ^ ksw) << 4));
; #pragma unroll
;       for (int ks = 0; ks < 12; ++ks) p0 = __builtin_amdgcn_mfma_f32_32x32x16_bf16(kf[ks], qr[ks], p0, 0, 0, 0);
;       SGB(0x100, 4); SGB(0x008, 2); SGB(0x100, 2); SGB(0x008, 2); SGB(0x100, 2); SGB(0x008, 2); SGB(0x100, 2); SGB(0x008, 2); SGB(0x100, 2); SGB(0x008, 4);
;     }
;     SBAR();
;     if (j + 1 < NT) BLOAD((j + 1) & 1, (j + 1) * 64);
;     SBAR();
;     {
;       trq<0, 0>(vb, fa);
;       bf16x8 kf[12];
; #pragma unroll
;       for (int ks = 0; ks < 12; ++ks) kf[ks] = *reinterpret_cast<const bf16x8*>(Ks + kq + 32 * 384 + (((ks * 2 + hi) ^ ksw) << 4));
; #pragma unroll
;       for (int ks = 0; ks < 12; ++ks) p1 = __builtin_amdgcn_mfma_f32_32x32x16_bf16(kf[ks], qr[ks], p1, 0, 0, 0);
;       sm_exp(p0, lsum); sm_pack(p0, pa0, pa1);
;     }
;     asm volatile("s_waitcnt lgkmcnt(0)" ::: "memory"); SBAR();
;     trq<0, 2>(vb, fb);
;     mmaq(o[0], o[1], fa, pa0, pa1);
;     sm_exp(p1, lsum);
.Lmla_skipdma_o:
	s_waitcnt lgkmcnt(9)
	v_mfma_f32_32x32x16_bf16 v[64:79], v[236:239], v[104:107], v[64:79]
	ds_read_b128 v[236:239], v169 offset:36864
	v_add_f32_e32 v182, v182, v83
	s_waitcnt lgkmcnt(9)
	v_mfma_f32_32x32x16_bf16 v[64:79], v[240:243], v[108:111], v[64:79]
	ds_read_b128 v[240:243], v170 offset:36864
	v_add_f32_e32 v182, v182, v84
	v_add_f32_e32 v182, v182, v85
	s_waitcnt lgkmcnt(9)
	v_mfma_f32_32x32x16_bf16 v[64:79], v[244:247], v[112:115], v[64:79]
	ds_read_b128 v[244:247], v171 offset:36864
	v_add_f32_e32 v182, v182, v86
	s_waitcnt lgkmcnt(9)
	v_mfma_f32_32x32x16_bf16 v[64:79], v[248:251], v[116:119], v[64:79]
	ds_read_b128 v[248:251], v172 offset:36864
	v_add_f32_e32 v182, v182, v87
	s_waitcnt lgkmcnt(9)
	v_mfma_f32_32x32x16_bf16 v[64:79], v[202:205], v[120:123], v[64:79]
	ds_read_b128 v[202:205], v169 offset:36992
	v_add_f32_e32 v182, v182, v88
	v_add_f32_e32 v182, v182, v89
	s_waitcnt lgkmcnt(9)
	v_mfma_f32_32x32x16_bf16 v[64:79], v[206:209], v[124:127], v[64:79]
	ds_read_b128 v[206:209], v170 offset:36992
	v_add_f32_e32 v182, v182, v90
	s_waitcnt lgkmcnt(9)
	v_mfma_f32_32x32x16_bf16 v[64:79], v[210:213], v[128:131], v[64:79]
	ds_read_b128 v[210:213], v171 offset:36992
	v_add_f32_e32 v182, v182, v91
	s_waitcnt lgkmcnt(9)
	v_mfma_f32_32x32x16_bf16 v[64:79], v[214:217], v[132:135], v[64:79]
	ds_read_b128 v[214:217], v172 offset:36992
	v_add_f32_e32 v182, v182, v92
	v_add_f32_e32 v182, v182, v93
	s_waitcnt lgkmcnt(9)
	v_mfma_f32_32x32x16_bf16 v[64:79], v[218:221], v[136:139], v[64:79]
	ds_read_b128 v[218:221], v169 offset:37120
	v_add_f32_e32 v182, v182, v94
	s_waitcnt lgkmcnt(9)
	v_mfma_f32_32x32x16_bf16 v[64:79], v[232:235], v[140:143], v[64:79]
	ds_read_b128 v[232:235], v170 offset:37120
	v_add_f32_e32 v182, v182, v95
	s_waitcnt lgkmcnt(9)
	v_mfma_f32_32x32x16_bf16 v[80:95], v[236:239], v[96:99], 0
	ds_read_b128 v[236:239], v171 offset:37120
	s_waitcnt lgkmcnt(9)
	v_mfma_f32_32x32x16_bf16 v[80:95], v[240:243], v[100:103], v[80:95]
	ds_read_b128 v[240:243], v172 offset:37120
	s_waitcnt lgkmcnt(9)
	v_mfma_f32_32x32x16_bf16 v[80:95], v[244:247], v[104:107], v[80:95]
	ds_read_b64_tr_b16 v[244:245], v166 offset:16384
	ds_read_b64_tr_b16 v[246:247], v166 offset:18432
	s_waitcnt lgkmcnt(10)
	v_mfma_f32_32x32x16_bf16 v[80:95], v[248:251], v[108:111], v[80:95]
	ds_read_b64_tr_b16 v[248:249], v166 offset:16896
	ds_read_b64_tr_b16 v[250:251], v166 offset:18944
	v_exp_f32_e32 v64, v64
	v_exp_f32_e32 v65, v65
	s_waitcnt lgkmcnt(11)
	v_mfma_f32_32x32x16_bf16 v[80:95], v[202:205], v[112:115], v[80:95]
	ds_read_b64_tr_b16 v[202:203], v166 offset:17408
	ds_read_b64_tr_b16 v[204:205], v166 offset:19456
	v_exp_f32_e32 v66, v66
	v_exp_f32_e32 v67, v67
	s_waitcnt lgkmcnt(12)
	v_mfma_f32_32x32x16_bf16 v[80:95], v[206:209], v[116:119], v[80:95]
	ds_read_b64_tr_b16 v[206:207], v166 offset:17920
	ds_read_b64_tr_b16 v[208:209], v166 offset:19968
	v_exp_f32_e32 v68, v68
	v_exp_f32_e32 v69, v69
	s_waitcnt lgkmcnt(13)
	v_mfma_f32_32x32x16_bf16 v[80:95], v[210:213], v[120:123], v[80:95]
	ds_read_b64_tr_b16 v[210:211], v166 offset:20480
	ds_read_b64_tr_b16 v[212:213], v166 offset:22528
	v_exp_f32_e32 v70, v70
	v_exp_f32_e32 v71, v71
	s_waitcnt lgkmcnt(14)
	v_mfma_f32_32x32x16_bf16 v[80:95], v[214:217], v[124:127], v[80:95]
	ds_read_b64_tr_b16 v[214:215], v166 offset:20992
	ds_read_b64_tr_b16 v[216:217], v166 offset:23040
	v_cvt_pk_bf16_f32 v174, v64, v65
	v_exp_f32_e32 v72, v72
	v_exp_f32_e32 v73, v73
	s_waitcnt lgkmcnt(14)
	v_mfma_f32_32x32x16_bf16 v[80:95], v[218:221], v[128:131], v[80:95]
	ds_read_b64_tr_b16 v[218:219], v166 offset:21504
	ds_read_b64_tr_b16 v[220:221], v166 offset:23552
	v_cvt_pk_bf16_f32 v175, v66, v67
	v_exp_f32_e32 v74, v74
	v_exp_f32_e32 v75, v75
	s_waitcnt lgkmcnt(14)
	v_mfma_f32_32x32x16_bf16 v[80:95], v[232:235], v[132:135], v[80:95]
	ds_read_b64_tr_b16 v[232:233], v166 offset:22016
	ds_read_b64_tr_b16 v[234:235], v166 offset:24064
	v_cvt_pk_bf16_f32 v176, v68, v69
	v_exp_f32_e32 v76, v76
	v_exp_f32_e32 v77, v77
	s_waitcnt lgkmcnt(14)
	v_mfma_f32_32x32x16_bf16 v[80:95], v[236:239], v[136:139], v[80:95]
	ds_read_b64_tr_b16 v[236:237], v166 offset:24576
	ds_read_b64_tr_b16 v[238:239], v166 offset:26624
	v_cvt_pk_bf16_f32 v177, v70, v71
	v_exp_f32_e32 v78, v78
	v_exp_f32_e32 v79, v79
	s_waitcnt lgkmcnt(14)
; #define SBAR() __builtin_amdgcn_sched_barrier(0)
; DEV void attn_b_item(const Params& P, int layer, int batch, int item, char* lds) {
;     ...
;       for (int ks = 0; ks < 12; ++ks) kf[ks] = *reinterpret_cast<const bf16x8*>(Ks + kq + 32 * 384 + (((ks * 2 + hi) ^ ksw) << 4));
; #pragma unroll
;       for (int ks = 0; ks < 12; ++ks) p1 = __builtin_amdgcn_mfma_f32_32x32x16_bf16(kf[ks], qr[ks], p1, 0, 0, 0);
;       sm_exp(p0, lsum); sm_pack(p0, pa0, pa1);
;     }
;     asm volatile("s_waitcnt lgkmcnt(0)" ::: "memory"); SBAR();
;     trq<0, 2>(vb, fb);
;     mmaq(o[0], o[1], fa, pa0, pa1);
;     sm_exp(p1, lsum);
;     asm volatile("s_waitcnt lgkmcnt(0)" ::: "memory"); SBAR();
;     trq<2, 0>(vb, fa);
;     mmaq(o[2], o[3], fb, pa0, pa1);
;     sm_pack(p1, pa2, pa3);
;     asm volatile("s_waitcnt lgkmcnt(0)" ::: "memory"); SBAR();
;     trq<2, 2>(vb, fb);
;     mmaq(o[0], o[1], fa, pa2, pa3);
;     asm volatile("s_waitcnt lgkmcnt(0)" ::: "memory"); SBAR();
;     mmaq(o[2], o[3], fb, pa2, pa3);
;     asm volatile("s_waitcnt vmcnt(0)" ::: "memory");
;     __syncthreads();
;   }
;     ...
;   lsum = swapsum(lsum);
	v_mfma_f32_32x32x16_bf16 v[80:95], v[240:243], v[140:143], v[80:95]
	ds_read_b64_tr_b16 v[240:241], v166 offset:25088
	ds_read_b64_tr_b16 v[242:243], v166 offset:27136
	v_cvt_pk_bf16_f32 v178, v72, v73
	v_cvt_pk_bf16_f32 v179, v74, v75
	v_cvt_pk_bf16_f32 v180, v76, v77
	v_cvt_pk_bf16_f32 v181, v78, v79
	s_waitcnt lgkmcnt(14)
	v_mfma_f32_32x32x16_bf16 v[48:63], v[174:177], v[244:247], v[48:63]
	ds_read_b64_tr_b16 v[244:245], v166 offset:25600
	ds_read_b64_tr_b16 v[246:247], v166 offset:27648
	v_add_f32_e32 v182, v182, v64
	v_add_f32_e32 v182, v182, v65
	v_add_f32_e32 v182, v182, v66
	v_add_f32_e32 v182, v182, v67
	s_waitcnt lgkmcnt(14)
	v_mfma_f32_32x32x16_bf16 v[32:47], v[174:177], v[248:251], v[32:47]
	ds_read_b64_tr_b16 v[248:249], v166 offset:26112
	ds_read_b64_tr_b16 v[250:251], v166 offset:28160
	v_add_f32_e32 v182, v182, v68
	v_add_f32_e32 v182, v182, v69
	v_add_f32_e32 v182, v182, v70
	v_add_f32_e32 v182, v182, v71
	s_waitcnt lgkmcnt(14)
	v_mfma_f32_32x32x16_bf16 v[16:31], v[174:177], v[202:205], v[16:31]
	ds_read_b64_tr_b16 v[202:203], v166 offset:28672
	ds_read_b64_tr_b16 v[204:205], v166 offset:30720
	v_add_f32_e32 v182, v182, v72
	v_add_f32_e32 v182, v182, v73
	v_add_f32_e32 v182, v182, v74
	v_add_f32_e32 v182, v182, v75
	s_waitcnt lgkmcnt(14)
	v_mfma_f32_32x32x16_bf16 v[0:15], v[174:177], v[206:209], v[0:15]
	ds_read_b64_tr_b16 v[206:207], v166 offset:29184
	ds_read_b64_tr_b16 v[208:209], v166 offset:31232
	v_exp_f32_e32 v80, v80
	v_exp_f32_e32 v81, v81
	v_exp_f32_e32 v82, v82
	s_waitcnt lgkmcnt(14)
	v_mfma_f32_32x32x16_bf16 v[48:63], v[178:181], v[210:213], v[48:63]
	ds_read_b64_tr_b16 v[210:211], v166 offset:29696
	ds_read_b64_tr_b16 v[212:213], v166 offset:31744
	v_exp_f32_e32 v83, v83
	v_exp_f32_e32 v84, v84
	v_exp_f32_e32 v85, v85
	s_waitcnt lgkmcnt(14)
	v_mfma_f32_32x32x16_bf16 v[32:47], v[178:181], v[214:217], v[32:47]
	ds_read_b64_tr_b16 v[214:215], v166 offset:30208
	ds_read_b64_tr_b16 v[216:217], v166 offset:32256
	v_exp_f32_e32 v86, v86
	v_exp_f32_e32 v87, v87
	v_exp_f32_e32 v88, v88
	s_waitcnt lgkmcnt(14)
	v_mfma_f32_32x32x16_bf16 v[16:31], v[178:181], v[218:221], v[16:31]
	v_cvt_pk_bf16_f32 v194, v80, v81
	v_cvt_pk_bf16_f32 v195, v82, v83
	v_exp_f32_e32 v89, v89
	v_exp_f32_e32 v90, v90
	v_exp_f32_e32 v91, v91
	s_waitcnt lgkmcnt(14)
	v_mfma_f32_32x32x16_bf16 v[0:15], v[178:181], v[232:235], v[0:15]
	v_cvt_pk_bf16_f32 v196, v84, v85
	v_cvt_pk_bf16_f32 v197, v86, v87
	v_exp_f32_e32 v92, v92
	v_exp_f32_e32 v93, v93
	s_waitcnt lgkmcnt(14)
	v_mfma_f32_32x32x16_bf16 v[48:63], v[194:197], v[236:239], v[48:63]
	v_exp_f32_e32 v94, v94
	v_exp_f32_e32 v95, v95
	s_waitcnt lgkmcnt(12)
	v_mfma_f32_32x32x16_bf16 v[32:47], v[194:197], v[240:243], v[32:47]
	v_cvt_pk_bf16_f32 v198, v88, v89
	v_cvt_pk_bf16_f32 v199, v90, v91
	v_add_f32_e32 v182, v182, v76
	v_add_f32_e32 v182, v182, v77
	s_waitcnt lgkmcnt(10)
	v_mfma_f32_32x32x16_bf16 v[16:31], v[194:197], v[244:247], v[16:31]
	v_cvt_pk_bf16_f32 v200, v92, v93
	v_cvt_pk_bf16_f32 v201, v94, v95
	v_add_f32_e32 v182, v182, v78
	v_add_f32_e32 v182, v182, v79
	s_waitcnt lgkmcnt(8)
	v_mfma_f32_32x32x16_bf16 v[0:15], v[194:197], v[248:251], v[0:15]
	s_waitcnt lgkmcnt(0)
	s_waitcnt vmcnt(0)
	s_barrier
	s_add_u32 s65, s65, 2
	s_cmp_lt_u32 s65, s50
	s_cbranch_scc1 .Lmla_loop
	v_mfma_f32_32x32x16_bf16 v[48:63], v[198:201], v[202:205], v[48:63]
	v_add_f32_e32 v182, v182, v80
	v_add_f32_e32 v182, v182, v81
	v_add_f32_e32 v182, v182, v82
	v_add_f32_e32 v182, v182, v83
	v_mfma_f32_32x32x16_bf16 v[32:47], v[198:201], v[206:209], v[32:47]
	v_add_f32_e32 v182, v182, v84
	v_add_f32_e32 v182, v182, v85
	v_add_f32_e32 v182, v182, v86
	v_add_f32_e32 v182, v182, v87
	v_mfma_f32_32x32x16_bf16 v[16:31], v[198:201], v[210:213], v[16:31]
	v_add_f32_e32 v182, v182, v88
	v_add_f32_e32 v182, v182, v89
	v_add_f32_e32 v182, v182, v90
	v_add_f32_e32 v182, v182, v91
	v_mfma_f32_32x32x16_bf16 v[0:15], v[198:201], v[214:217], v[0:15]
	v_add_f32_e32 v182, v182, v92
	v_add_f32_e32 v182, v182, v93
	v_add_f32_e32 v182, v182, v94
	v_add_f32_e32 v182, v182, v95
